# GU2 weight conversion moved to the end of P8 (all workgroups) so FFN2 gate/up weights are last-level-cache fresh for P10; P4 tail no longer converts
# baseline (speedup 1.0000x reference)
; __device__ __forceinline__ unsigned cvt_pk_bf16(float lo, float hi) { unsigned r; asm volatile("v_cvt_pk_bf16_f32 %0, %1, %2" : "=v"(r) : "v"(lo), "v"(hi)); return r; }
; __global__ void __launch_bounds__(NTHREADS, 2) fwd_kernel(Params P) {
;     ...
;         for (int it = gw; it < IT_TOTAL; it += NGW) {
;             int r = it; const float* W; bf16_t* WT; int N, ldk, mode = 0; const float* fg = nullptr; const float* fb = nullptr; float* cs = nullptr;
;             if (r < IT_GU) { W = P.in[I_WIN]; WT = WIN; N = NZ; ldk = D; fg = P.in[I_LN1G]; fb = P.in[I_LN1B]; cs = CSUM; }
;             else if ((r -= IT_GU) < IT_SQ) { W = P.in[I_WKV]; WT = WKV; N = D; ldk = D; }
;             else if ((r -= IT_SQ) < 3 * IT_BR) { const int k = r / IT_BR; r -= k * IT_BR; W = P.in[I_WBR] + (size_t)k * BW * D; WT = WBR + (size_t)k * D * BW; N = D; ldk = BW; }
;             else if ((r -= 3 * IT_BR) < IT_SQ) { W = P.in[I_WOUT]; WT = WOUT; N = D; ldk = D; }
;             else if ((r -= IT_SQ) < IT_GU) { W = P.in[I_GU2]; WT = WGU2; N = NZ; ldk = D; mode = 1; fg = P.in[I_LN2G]; fb = P.in[I_LN2B]; cs = CSUM + 2 * NZ; }
;             else if ((r -= IT_GU) < IT_DN) { W = P.in[I_DN2]; WT = WD2; N = D; ldk = FF; }
;             else if ((r -= IT_DN) < 16 * IT_LR) { const int m = r / IT_LR; r -= m * IT_LR; const int k = m >> 1, x = m & 1;
;                 W = (x ? P.in[I_LWX] : P.in[I_LWA]) + (size_t)k * 128 * 128; WT = WLRU + (size_t)k * 256 * 128 + x * 128 * 128; N = 128; ldk = 128; }
;             else if ((r -= 16 * IT_LR) < IT_DN) { W = P.in[I_DN1]; WT = WD1; N = D; ldk = FF; }
;             else { r -= IT_DN; W = P.in[I_GU1]; WT = WGU1; N = NZ; ldk = D; mode = 1; }
;             const int nblk = N / 32, kb = r / nblk, nb = r % nblk, n0 = 32 * nb;
;             int dr = n0;
;             if (mode == 1) dr = (n0 < FF) ? (n0 / 128) * 256 + (n0 % 128) : ((n0 - FF) / 128) * 256 + 128 + ((n0 - FF) % 128);
;             transpose_item(W, N, WT, ldk, 64 * kb, n0, dr, scr, lane, fg, fb, cs);
;         }
;         for (int i = gw * 64 + lane; i < 4 * 128 * 128; i += NGW * 64) { const int t = (i >> 7) & 127, s = i & 127; const float w = P.in[I_WS][i]; WSP[i] = (bf16_t)(cvt_pk_bf16(s <= t ? w : 0.f, 0.f) & 0xffffu); }
.Lcv_exit:
	s_cmp_lg_u32 s100, 0
	s_cbranch_scc1 .Lcv_d1
	s_mov_b32 s100, 1
	s_mov_b32 s98, 0xcc7f
	v_readlane_b32 s99, v255, 13
	s_lshl_b32 s101, s34, 3
	s_nop 3
	s_add_i32 s99, s99, s101
	s_add_i32 s99, s99, 0x400
	s_and_b32 s99, s99, 0x7ff
	s_add_i32 s30, s99, 0x8a00
	s_branch .Lcv_entry
.Lcv_d1:
	s_cmp_lg_u32 s100, 1
	s_cbranch_scc1 .Lcv_d2
	v_readlane_b32 s99, v255, 13
	s_lshl_b32 s101, s34, 3
	s_nop 3
	s_add_i32 s99, s99, s101
	s_mov_b32 s30, s99
	s_branch .LBB0_62
.Lcv_d2:
	s_cmp_lg_u32 s100, 2
	s_cbranch_scc0 .Lcv_ret_p1
	s_cmp_lg_u32 s100, 3
	s_cbranch_scc1 .Lcv_n1
	s_branch .Lcv_hop_ret_p8all
.Lcv_n1:
	s_branch .Lcv_hop_ret_p10
.LBB0_62:
	s_waitcnt vmcnt(5)
	v_lshl_or_b32 v2, s30, 6, v237
	s_mov_b32 s0, 0x10000
	v_cmp_gt_i32_e32 vcc, s0, v2
	s_and_saveexec_b64 s[4:5], vcc
	s_cbranch_execz .LBB0_65
	s_lshl_b32 s8, s94, 9
	v_ashrrev_i32_e32 v3, 31, v2
	v_readlane_b32 s12, v254, 11
	v_readlane_b32 s13, v254, 12
	v_readlane_b32 s14, v254, 13
	v_readlane_b32 s15, v254, 14
	v_readlane_b32 s26, v254, 25
	v_readlane_b32 s27, v254, 26
	s_ashr_i32 s9, s8, 31
	s_waitcnt vmcnt(4)
	v_lshl_add_u64 v[6:7], v[2:3], 1, s[92:93]
	s_mov_b64 s[0:1], 0xcc80000
	s_waitcnt lgkmcnt(0)
	v_lshl_add_u64 v[4:5], v[2:3], 2, s[26:27]
	s_lshl_b64 s[10:11], s[8:9], 2
	v_lshl_add_u64 v[6:7], v[6:7], 0, s[0:1]
	s_lshl_b64 s[12:13], s[8:9], 1
	s_mov_b64 s[14:15], 0
	v_mov_b32_e32 v1, 0
	s_mov_b32 s2, 0xffff
	v_readlane_b32 s16, v254, 15
	v_readlane_b32 s17, v254, 16
	v_readlane_b32 s18, v254, 17
	v_readlane_b32 s19, v254, 18
	v_readlane_b32 s20, v254, 19
	v_readlane_b32 s21, v254, 20
	v_readlane_b32 s22, v254, 21
	v_readlane_b32 s23, v254, 22
	v_readlane_b32 s24, v254, 23
	v_readlane_b32 s25, v254, 24

; __global__ void __launch_bounds__(NTHREADS, 2) fwd_kernel(Params P) {
;     ...
;         for (int it = gw; it < IT_TOTAL; it += NGW) {
;             int r = it; const float* W; bf16_t* WT; int N, ldk, mode = 0; const float* fg = nullptr; const float* fb = nullptr; float* cs = nullptr;
;             if (r < IT_GU) { W = P.in[I_WIN]; WT = WIN; N = NZ; ldk = D; fg = P.in[I_LN1G]; fb = P.in[I_LN1B]; cs = CSUM; }
;             else if ((r -= IT_GU) < IT_SQ) { W = P.in[I_WKV]; WT = WKV; N = D; ldk = D; }
;             else if ((r -= IT_SQ) < 3 * IT_BR) { const int k = r / IT_BR; r -= k * IT_BR; W = P.in[I_WBR] + (size_t)k * BW * D; WT = WBR + (size_t)k * D * BW; N = D; ldk = BW; }
;             else if ((r -= 3 * IT_BR) < IT_SQ) { W = P.in[I_WOUT]; WT = WOUT; N = D; ldk = D; }
;             else if ((r -= IT_SQ) < IT_GU) { W = P.in[I_GU2]; WT = WGU2; N = NZ; ldk = D; mode = 1; fg = P.in[I_LN2G]; fb = P.in[I_LN2B]; cs = CSUM + 2 * NZ; }
;             else if ((r -= IT_GU) < IT_DN) { W = P.in[I_DN2]; WT = WD2; N = D; ldk = FF; }
;             else if ((r -= IT_DN) < 16 * IT_LR) { const int m = r / IT_LR; r -= m * IT_LR; const int k = m >> 1, x = m & 1;
;                 W = (x ? P.in[I_LWX] : P.in[I_LWA]) + (size_t)k * 128 * 128; WT = WLRU + (size_t)k * 256 * 128 + x * 128 * 128; N = 128; ldk = 128; }
;             else if ((r -= 16 * IT_LR) < IT_DN) { W = P.in[I_DN1]; WT = WD1; N = D; ldk = FF; }
;             else { r -= IT_DN; W = P.in[I_GU1]; WT = WGU1; N = NZ; ldk = D; mode = 1; }
;             const int nblk = N / 32, kb = r / nblk, nb = r % nblk, n0 = 32 * nb;
;             int dr = n0;
;             if (mode == 1) dr = (n0 < FF) ? (n0 / 128) * 256 + (n0 % 128) : ((n0 - FF) / 128) * 256 + 128 + ((n0 - FF) % 128);
;             transpose_item(W, N, WT, ldk, 64 * kb, n0, dr, scr, lane, fg, fb, cs);
;         }
.LBB0_162:
	s_cmp_lt_u32 s34, 172
	s_cbranch_scc1 .Lcv_skip_p1
	v_writelane_b32 v252, s0, 0
	v_writelane_b32 v252, s1, 1
	v_writelane_b32 v252, s2, 2
	v_writelane_b32 v252, s3, 3
	v_writelane_b32 v252, s4, 4
	v_writelane_b32 v252, s5, 5
	v_writelane_b32 v252, s6, 6
	v_writelane_b32 v252, s7, 7
	v_writelane_b32 v252, s8, 8
	v_writelane_b32 v252, s9, 9
	v_writelane_b32 v252, s10, 10
	v_writelane_b32 v252, s11, 11
	v_writelane_b32 v252, s12, 12
	v_writelane_b32 v252, s13, 13
	v_writelane_b32 v252, s14, 14
	v_writelane_b32 v252, s15, 15
	v_writelane_b32 v252, s16, 16
	v_writelane_b32 v252, s17, 17
	v_writelane_b32 v252, s18, 18
	v_writelane_b32 v252, s19, 19
	v_writelane_b32 v252, s20, 20
	v_writelane_b32 v252, s21, 21
	v_writelane_b32 v252, s22, 22
	v_writelane_b32 v252, s23, 23
	v_writelane_b32 v252, s24, 24
	v_writelane_b32 v252, s25, 25
	v_writelane_b32 v252, s26, 26
	v_writelane_b32 v252, s27, 27
	v_writelane_b32 v252, s28, 28
	v_writelane_b32 v252, s29, 29
	v_writelane_b32 v252, s30, 30
	v_writelane_b32 v252, s31, 31
	v_writelane_b32 v252, s32, 32
	v_writelane_b32 v252, s33, 33
	v_writelane_b32 v252, s34, 34
	v_writelane_b32 v252, s35, 35
	v_writelane_b32 v252, s36, 36
	v_writelane_b32 v252, s37, 37
	v_writelane_b32 v252, s38, 38
	v_writelane_b32 v252, s39, 39
	v_writelane_b32 v252, s40, 40
	v_writelane_b32 v252, s41, 41
	v_writelane_b32 v252, s42, 42
	v_writelane_b32 v252, s43, 43
	v_writelane_b32 v252, s44, 44
	v_writelane_b32 v252, s45, 45
	v_writelane_b32 v252, s46, 46
	v_writelane_b32 v252, s47, 47
	v_writelane_b32 v252, s48, 48
	v_writelane_b32 v252, s49, 49
	v_writelane_b32 v252, s50, 50
	v_writelane_b32 v252, s51, 51
	v_writelane_b32 v252, s52, 52
	v_writelane_b32 v252, s53, 53
	v_writelane_b32 v252, s54, 54
	v_writelane_b32 v252, s55, 55
	v_writelane_b32 v252, s56, 56
	v_writelane_b32 v252, s57, 57
	v_writelane_b32 v252, s58, 58
	v_writelane_b32 v252, s59, 59
	v_writelane_b32 v252, s60, 60
	v_writelane_b32 v252, s61, 61
	v_writelane_b32 v252, s62, 62
	v_writelane_b32 v252, s63, 63
	v_writelane_b32 v253, s64, 0
	v_writelane_b32 v253, s65, 1
	v_writelane_b32 v253, s66, 2
	v_writelane_b32 v253, s67, 3
	v_writelane_b32 v253, s68, 4
	v_writelane_b32 v253, s69, 5
	v_writelane_b32 v253, s70, 6
	v_writelane_b32 v253, s71, 7
	v_writelane_b32 v253, s72, 8
	v_writelane_b32 v253, s73, 9
	v_writelane_b32 v253, s74, 10
	v_writelane_b32 v253, s75, 11
	v_writelane_b32 v253, s76, 12
	v_writelane_b32 v253, s77, 13
	v_writelane_b32 v253, s78, 14
	v_writelane_b32 v253, s79, 15
	v_writelane_b32 v253, s80, 16
	v_writelane_b32 v253, s81, 17
	v_writelane_b32 v253, s82, 18
	v_writelane_b32 v253, s83, 19
	v_writelane_b32 v253, s84, 20
	v_writelane_b32 v253, s85, 21
	v_writelane_b32 v253, s86, 22
	v_writelane_b32 v253, s87, 23
	v_writelane_b32 v253, s88, 24
	v_writelane_b32 v253, s89, 25
	v_writelane_b32 v253, s90, 26
	v_writelane_b32 v253, s91, 27
	v_writelane_b32 v253, s92, 28
	v_writelane_b32 v253, s93, 29
	v_writelane_b32 v253, s94, 30
	v_writelane_b32 v253, s95, 31
	v_writelane_b32 v253, s96, 32
	v_writelane_b32 v253, s97, 33
	s_mov_b32 s100, 2
	s_mov_b32 s98, 0x47ff
	v_and_b32_e32 v237, 63, v178
	v_readlane_b32 s99, v255, 13
	v_readfirstlane_b32 s37, v178
	s_nop 4
	s_sub_i32 s101, s34, 172
	s_lshl_b32 s101, s101, 3
	s_add_i32 s99, s99, s101
	s_add_i32 s30, s99, 0x2c00
	s_movk_i32 s86, 672
	s_branch .Lcv_entry

; __global__ void __launch_bounds__(NTHREADS, 2) fwd_kernel(Params P) {
;     ...
;         for (int it = gw; it < IT_TOTAL; it += NGW) {
;             int r = it; const float* W; bf16_t* WT; int N, ldk, mode = 0; const float* fg = nullptr; const float* fb = nullptr; float* cs = nullptr;
;             if (r < IT_GU) { W = P.in[I_WIN]; WT = WIN; N = NZ; ldk = D; fg = P.in[I_LN1G]; fb = P.in[I_LN1B]; cs = CSUM; }
;             else if ((r -= IT_GU) < IT_SQ) { W = P.in[I_WKV]; WT = WKV; N = D; ldk = D; }
;             else if ((r -= IT_SQ) < 3 * IT_BR) { const int k = r / IT_BR; r -= k * IT_BR; W = P.in[I_WBR] + (size_t)k * BW * D; WT = WBR + (size_t)k * D * BW; N = D; ldk = BW; }
;             else if ((r -= 3 * IT_BR) < IT_SQ) { W = P.in[I_WOUT]; WT = WOUT; N = D; ldk = D; }
;             else if ((r -= IT_SQ) < IT_GU) { W = P.in[I_GU2]; WT = WGU2; N = NZ; ldk = D; mode = 1; fg = P.in[I_LN2G]; fb = P.in[I_LN2B]; cs = CSUM + 2 * NZ; }
;             else if ((r -= IT_GU) < IT_DN) { W = P.in[I_DN2]; WT = WD2; N = D; ldk = FF; }
;             else if ((r -= IT_DN) < 16 * IT_LR) { const int m = r / IT_LR; r -= m * IT_LR; const int k = m >> 1, x = m & 1;
;                 W = (x ? P.in[I_LWX] : P.in[I_LWA]) + (size_t)k * 128 * 128; WT = WLRU + (size_t)k * 256 * 128 + x * 128 * 128; N = 128; ldk = 128; }
;             else if ((r -= 16 * IT_LR) < IT_DN) { W = P.in[I_DN1]; WT = WD1; N = D; ldk = FF; }
;             else { r -= IT_DN; W = P.in[I_GU1]; WT = WGU1; N = NZ; ldk = D; mode = 1; }
;             const int nblk = N / 32, kb = r / nblk, nb = r % nblk, n0 = 32 * nb;
;             int dr = n0;
;             if (mode == 1) dr = (n0 < FF) ? (n0 / 128) * 256 + (n0 % 128) : ((n0 - FF) / 128) * 256 + 128 + ((n0 - FF) % 128);
;             transpose_item(W, N, WT, ldk, 64 * kb, n0, dr, scr, lane, fg, fb, cs);
;         }
.LBB0_968:
	s_cmp_lt_u32 s34, 0
	s_cbranch_scc1 .Lcv_skip_p8all
	v_writelane_b32 v252, s0, 0
	v_writelane_b32 v252, s1, 1
	v_writelane_b32 v252, s2, 2
	v_writelane_b32 v252, s3, 3
	v_writelane_b32 v252, s4, 4
	v_writelane_b32 v252, s5, 5
	v_writelane_b32 v252, s6, 6
	v_writelane_b32 v252, s7, 7
	v_writelane_b32 v252, s8, 8
	v_writelane_b32 v252, s9, 9
	v_writelane_b32 v252, s10, 10
	v_writelane_b32 v252, s11, 11
	v_writelane_b32 v252, s12, 12
	v_writelane_b32 v252, s13, 13
	v_writelane_b32 v252, s14, 14
	v_writelane_b32 v252, s15, 15
	v_writelane_b32 v252, s16, 16
	v_writelane_b32 v252, s17, 17
	v_writelane_b32 v252, s18, 18
	v_writelane_b32 v252, s19, 19
	v_writelane_b32 v252, s20, 20
	v_writelane_b32 v252, s21, 21
	v_writelane_b32 v252, s22, 22
	v_writelane_b32 v252, s23, 23
	v_writelane_b32 v252, s24, 24
	v_writelane_b32 v252, s25, 25
	v_writelane_b32 v252, s26, 26
	v_writelane_b32 v252, s27, 27
	v_writelane_b32 v252, s28, 28
	v_writelane_b32 v252, s29, 29
	v_writelane_b32 v252, s30, 30
	v_writelane_b32 v252, s31, 31
	v_writelane_b32 v252, s32, 32
	v_writelane_b32 v252, s33, 33
	v_writelane_b32 v252, s34, 34
	v_writelane_b32 v252, s35, 35
	v_writelane_b32 v252, s36, 36
	v_writelane_b32 v252, s37, 37
	v_writelane_b32 v252, s38, 38
	v_writelane_b32 v252, s39, 39
	v_writelane_b32 v252, s40, 40
	v_writelane_b32 v252, s41, 41
	v_writelane_b32 v252, s42, 42
	v_writelane_b32 v252, s43, 43
	v_writelane_b32 v252, s44, 44
	v_writelane_b32 v252, s45, 45
	v_writelane_b32 v252, s46, 46
	v_writelane_b32 v252, s47, 47
	v_writelane_b32 v252, s48, 48
	v_writelane_b32 v252, s49, 49
	v_writelane_b32 v252, s50, 50
	v_writelane_b32 v252, s51, 51
	v_writelane_b32 v252, s52, 52
	v_writelane_b32 v252, s53, 53
	v_writelane_b32 v252, s54, 54
	v_writelane_b32 v252, s55, 55
	v_writelane_b32 v252, s56, 56
	v_writelane_b32 v252, s57, 57
	v_writelane_b32 v252, s58, 58
	v_writelane_b32 v252, s59, 59
	v_writelane_b32 v252, s60, 60
	v_writelane_b32 v252, s61, 61
	v_writelane_b32 v252, s62, 62
	v_writelane_b32 v252, s63, 63
	v_writelane_b32 v253, s64, 0
	v_writelane_b32 v253, s65, 1
	v_writelane_b32 v253, s66, 2
	v_writelane_b32 v253, s67, 3
	v_writelane_b32 v253, s68, 4
	v_writelane_b32 v253, s69, 5
	v_writelane_b32 v253, s70, 6
	v_writelane_b32 v253, s71, 7
	v_writelane_b32 v253, s72, 8
	v_writelane_b32 v253, s73, 9
	v_writelane_b32 v253, s74, 10
	v_writelane_b32 v253, s75, 11
	v_writelane_b32 v253, s76, 12
	v_writelane_b32 v253, s77, 13
	v_writelane_b32 v253, s78, 14
	v_writelane_b32 v253, s79, 15
	v_writelane_b32 v253, s80, 16
	v_writelane_b32 v253, s81, 17
	v_writelane_b32 v253, s82, 18
	v_writelane_b32 v253, s83, 19
	v_writelane_b32 v253, s84, 20
	v_writelane_b32 v253, s85, 21
	v_writelane_b32 v253, s86, 22
	v_writelane_b32 v253, s87, 23
	v_writelane_b32 v253, s88, 24
	v_writelane_b32 v253, s89, 25
	v_writelane_b32 v253, s90, 26
	v_writelane_b32 v253, s91, 27
	v_writelane_b32 v253, s92, 28
	v_writelane_b32 v253, s93, 29
	v_writelane_b32 v253, s94, 30
	v_writelane_b32 v253, s95, 31
	v_writelane_b32 v253, s96, 32
	v_writelane_b32 v253, s97, 33
	s_mov_b32 s100, 3
	s_mov_b32 s98, 0x73ff
	v_and_b32_e32 v237, 63, v178
	v_readlane_b32 s99, v255, 13
	v_readfirstlane_b32 s37, v178
	s_nop 4
	s_sub_i32 s101, s34, 0
	s_lshl_b32 s101, s101, 3
	s_add_i32 s99, s99, s101
	s_add_i32 s30, s99, 0x4800
	s_movk_i32 s86, 2048
	s_branch .Lcv_hop_entry
; __device__ __forceinline__ unsigned xb_add(unsigned* p, unsigned v) { return __hip_atomic_fetch_add(p, v, __ATOMIC_RELAXED, __HIP_MEMORY_SCOPE_AGENT); }
; __device__ __forceinline__ void xcd_barrier(const XcdBarrier& b) {
;     asm volatile("s_waitcnt vmcnt(0)" ::: "memory");
;     __syncthreads();
;     if (threadIdx.x == 0) {
;         unsigned* bar = b.bar;
;         __builtin_amdgcn_s_waitcnt(0);
;         unsigned nloc = b.st[0], nx = b.st[1];
;         if (nloc == 0u) { xcd_barrier_complete(bar, b.x, nloc, nx); b.st[0] = nloc; b.st[1] = nx; }
;         const unsigned old = xb_add(&bar[XB_XSUB(b.x)], 1u);
.Lcv_ret_p8all:
	v_readlane_b32 s0, v252, 0
	v_readlane_b32 s1, v252, 1
	v_readlane_b32 s2, v252, 2
	v_readlane_b32 s3, v252, 3
	v_readlane_b32 s4, v252, 4
	v_readlane_b32 s5, v252, 5
	v_readlane_b32 s6, v252, 6
	v_readlane_b32 s7, v252, 7
	v_readlane_b32 s8, v252, 8
	v_readlane_b32 s9, v252, 9
	v_readlane_b32 s10, v252, 10
	v_readlane_b32 s11, v252, 11
	v_readlane_b32 s12, v252, 12
	v_readlane_b32 s13, v252, 13
	v_readlane_b32 s14, v252, 14
	v_readlane_b32 s15, v252, 15
	v_readlane_b32 s16, v252, 16
	v_readlane_b32 s17, v252, 17
	v_readlane_b32 s18, v252, 18
	v_readlane_b32 s19, v252, 19
	v_readlane_b32 s20, v252, 20
	v_readlane_b32 s21, v252, 21
	v_readlane_b32 s22, v252, 22
	v_readlane_b32 s23, v252, 23
	v_readlane_b32 s24, v252, 24
	v_readlane_b32 s25, v252, 25
	v_readlane_b32 s26, v252, 26
	v_readlane_b32 s27, v252, 27
	v_readlane_b32 s28, v252, 28
	v_readlane_b32 s29, v252, 29
	v_readlane_b32 s30, v252, 30
	v_readlane_b32 s31, v252, 31
	v_readlane_b32 s32, v252, 32
	v_readlane_b32 s33, v252, 33
	v_readlane_b32 s34, v252, 34
	v_readlane_b32 s35, v252, 35
	v_readlane_b32 s36, v252, 36
	v_readlane_b32 s37, v252, 37
	v_readlane_b32 s38, v252, 38
	v_readlane_b32 s39, v252, 39
	v_readlane_b32 s40, v252, 40
	v_readlane_b32 s41, v252, 41
	v_readlane_b32 s42, v252, 42
	v_readlane_b32 s43, v252, 43
	v_readlane_b32 s44, v252, 44
	v_readlane_b32 s45, v252, 45
	v_readlane_b32 s46, v252, 46
	v_readlane_b32 s47, v252, 47
	v_readlane_b32 s48, v252, 48
	v_readlane_b32 s49, v252, 49
	v_readlane_b32 s50, v252, 50
	v_readlane_b32 s51, v252, 51
	v_readlane_b32 s52, v252, 52
	v_readlane_b32 s53, v252, 53
	v_readlane_b32 s54, v252, 54
	v_readlane_b32 s55, v252, 55
	v_readlane_b32 s56, v252, 56
	v_readlane_b32 s57, v252, 57
	v_readlane_b32 s58, v252, 58
	v_readlane_b32 s59, v252, 59
	v_readlane_b32 s60, v252, 60
	v_readlane_b32 s61, v252, 61
	v_readlane_b32 s62, v252, 62
	v_readlane_b32 s63, v252, 63
	v_readlane_b32 s64, v253, 0
	v_readlane_b32 s65, v253, 1
	v_readlane_b32 s66, v253, 2
	v_readlane_b32 s67, v253, 3
	v_readlane_b32 s68, v253, 4
	v_readlane_b32 s69, v253, 5
	v_readlane_b32 s70, v253, 6
	v_readlane_b32 s71, v253, 7
	v_readlane_b32 s72, v253, 8
	v_readlane_b32 s73, v253, 9
	v_readlane_b32 s74, v253, 10
	v_readlane_b32 s75, v253, 11
	v_readlane_b32 s76, v253, 12
	v_readlane_b32 s77, v253, 13
	v_readlane_b32 s78, v253, 14
	v_readlane_b32 s79, v253, 15
	v_readlane_b32 s80, v253, 16
	v_readlane_b32 s81, v253, 17
	v_readlane_b32 s82, v253, 18
	v_readlane_b32 s83, v253, 19
	v_readlane_b32 s84, v253, 20
	v_readlane_b32 s85, v253, 21
	v_readlane_b32 s86, v253, 22
	v_readlane_b32 s87, v253, 23
	v_readlane_b32 s88, v253, 24
	v_readlane_b32 s89, v253, 25
	v_readlane_b32 s90, v253, 26
	v_readlane_b32 s91, v253, 27
	v_readlane_b32 s92, v253, 28
	v_readlane_b32 s93, v253, 29
	v_readlane_b32 s94, v253, 30
	v_readlane_b32 s95, v253, 31
	v_readlane_b32 s96, v253, 32
	v_readlane_b32 s97, v253, 33
	s_nop 4
.Lcv_skip_p8all:
	s_waitcnt vmcnt(0)
	s_waitcnt lgkmcnt(0)
	s_barrier
	s_mov_b64 s[0:1], exec
	v_readlane_b32 s2, v254, 9
	v_readlane_b32 s3, v254, 10
	s_and_b64 s[2:3], s[0:1], s[2:3]
	s_mov_b32 s62, s56
	s_mov_b64 exec, s[2:3]
	s_cbranch_execz .LBB0_1020
	s_add_i32 s2, 0, 0x26fc0
	v_mov_b32_e32 v0, s2
	s_waitcnt vmcnt(0) expcnt(0) lgkmcnt(0)
	ds_read_b32 v2, v0
	s_add_i32 s2, 0, 0x26fc4
	v_mov_b32_e32 v0, s2
	ds_read_b32 v0, v0
	s_waitcnt lgkmcnt(1)
	v_cmp_ne_u32_e32 vcc, 0, v2
	s_cbranch_vccnz .LBB0_984
	s_add_u32 s4, s92, 0x2b1a0200
	s_addc_u32 s5, s93, 0
	s_add_u32 s12, s92, 0x2b1a0400
	s_addc_u32 s13, s93, 0
	s_add_u32 s14, s92, 0x2b1a0500
	s_addc_u32 s15, s93, 0
	s_add_u32 s16, s92, 0x2b1a0600
	s_addc_u32 s17, s93, 0
	s_add_u32 s18, s92, 0x2b1a0700
	s_addc_u32 s19, s93, 0
	s_add_u32 s20, s92, 0x2b1a0800
	s_addc_u32 s21, s93, 0
	s_add_u32 s22, s92, 0x2b1a0900
	s_addc_u32 s23, s93, 0
	s_add_u32 s24, s92, 0x2b1a0a00
	s_addc_u32 s25, s93, 0
	s_add_u32 s26, s92, 0x2b1a0b00
	s_addc_u32 s27, s93, 0
	s_add_u32 s28, s92, 0x2b1a0c00
	s_addc_u32 s29, s93, 0
	s_add_u32 s36, s92, 0x2b1a0d00
	s_addc_u32 s37, s93, 0
	s_add_u32 s42, s92, 0x2b1a0e00
	s_addc_u32 s43, s93, 0
	s_add_u32 s44, s92, 0x2b1a0f00
	s_addc_u32 s45, s93, 0
	s_add_u32 s46, s92, 0x2b1a1000
	s_addc_u32 s47, s93, 0
	s_add_u32 s48, s92, 0x2b1a1100
	s_addc_u32 s49, s93, 0
	v_readlane_b32 s2, v254, 43
	s_add_u32 s52, s92, 0x2b1a1200
	v_readlane_b32 s2, v254, 8
	s_addc_u32 s53, s93, 0
	v_readlane_b32 s3, v254, 44
	s_mul_i32 s2, s95, s2
	s_add_u32 s54, s92, 0x2b1a1300
	s_mul_i32 s2, s2, s94
	s_addc_u32 s55, s93, 0
	s_mov_b32 s3, 1
	v_mov_b32_e32 v16, 0
	s_branch .LBB0_972

; __global__ void __launch_bounds__(NTHREADS, 2) fwd_kernel(Params P) {
;     ...
;         for (int it = gw; it < IT_TOTAL; it += NGW) {
;             int r = it; const float* W; bf16_t* WT; int N, ldk, mode = 0; const float* fg = nullptr; const float* fb = nullptr; float* cs = nullptr;
;             if (r < IT_GU) { W = P.in[I_WIN]; WT = WIN; N = NZ; ldk = D; fg = P.in[I_LN1G]; fb = P.in[I_LN1B]; cs = CSUM; }
;             else if ((r -= IT_GU) < IT_SQ) { W = P.in[I_WKV]; WT = WKV; N = D; ldk = D; }
;             else if ((r -= IT_SQ) < 3 * IT_BR) { const int k = r / IT_BR; r -= k * IT_BR; W = P.in[I_WBR] + (size_t)k * BW * D; WT = WBR + (size_t)k * D * BW; N = D; ldk = BW; }
;             else if ((r -= 3 * IT_BR) < IT_SQ) { W = P.in[I_WOUT]; WT = WOUT; N = D; ldk = D; }
;             else if ((r -= IT_SQ) < IT_GU) { W = P.in[I_GU2]; WT = WGU2; N = NZ; ldk = D; mode = 1; fg = P.in[I_LN2G]; fb = P.in[I_LN2B]; cs = CSUM + 2 * NZ; }
;             else if ((r -= IT_GU) < IT_DN) { W = P.in[I_DN2]; WT = WD2; N = D; ldk = FF; }
;             else if ((r -= IT_DN) < 16 * IT_LR) { const int m = r / IT_LR; r -= m * IT_LR; const int k = m >> 1, x = m & 1;
;                 W = (x ? P.in[I_LWX] : P.in[I_LWA]) + (size_t)k * 128 * 128; WT = WLRU + (size_t)k * 256 * 128 + x * 128 * 128; N = 128; ldk = 128; }
;             else if ((r -= 16 * IT_LR) < IT_DN) { W = P.in[I_DN1]; WT = WD1; N = D; ldk = FF; }
;             else { r -= IT_DN; W = P.in[I_GU1]; WT = WGU1; N = NZ; ldk = D; mode = 1; }
;             const int nblk = N / 32, kb = r / nblk, nb = r % nblk, n0 = 32 * nb;
;             int dr = n0;
;             if (mode == 1) dr = (n0 < FF) ? (n0 / 128) * 256 + (n0 % 128) : ((n0 - FF) / 128) * 256 + 128 + ((n0 - FF) % 128);
;             transpose_item(W, N, WT, ldk, 64 * kb, n0, dr, scr, lane, fg, fb, cs);
.LBB0_1044:
	s_cmp_lt_u32 s34, 172
	s_cbranch_scc1 .Lcv_skip_p10
	v_writelane_b32 v252, s0, 0
	v_writelane_b32 v252, s1, 1
	v_writelane_b32 v252, s2, 2
	v_writelane_b32 v252, s3, 3
	v_writelane_b32 v252, s4, 4
	v_writelane_b32 v252, s5, 5
	v_writelane_b32 v252, s6, 6
	v_writelane_b32 v252, s7, 7
	v_writelane_b32 v252, s8, 8
	v_writelane_b32 v252, s9, 9
	v_writelane_b32 v252, s10, 10
	v_writelane_b32 v252, s11, 11
	v_writelane_b32 v252, s12, 12
	v_writelane_b32 v252, s13, 13
	v_writelane_b32 v252, s14, 14
	v_writelane_b32 v252, s15, 15
	v_writelane_b32 v252, s16, 16
	v_writelane_b32 v252, s17, 17
	v_writelane_b32 v252, s18, 18
	v_writelane_b32 v252, s19, 19
	v_writelane_b32 v252, s20, 20
	v_writelane_b32 v252, s21, 21
	v_writelane_b32 v252, s22, 22
	v_writelane_b32 v252, s23, 23
	v_writelane_b32 v252, s24, 24
	v_writelane_b32 v252, s25, 25
	v_writelane_b32 v252, s26, 26
	v_writelane_b32 v252, s27, 27
	v_writelane_b32 v252, s28, 28
	v_writelane_b32 v252, s29, 29
	v_writelane_b32 v252, s30, 30
	v_writelane_b32 v252, s31, 31
	v_writelane_b32 v252, s32, 32
	v_writelane_b32 v252, s33, 33
	v_writelane_b32 v252, s34, 34
	v_writelane_b32 v252, s35, 35
	v_writelane_b32 v252, s36, 36
	v_writelane_b32 v252, s37, 37
	v_writelane_b32 v252, s38, 38
	v_writelane_b32 v252, s39, 39
	v_writelane_b32 v252, s40, 40
	v_writelane_b32 v252, s41, 41
	v_writelane_b32 v252, s42, 42
	v_writelane_b32 v252, s43, 43
	v_writelane_b32 v252, s44, 44
	v_writelane_b32 v252, s45, 45
	v_writelane_b32 v252, s46, 46
	v_writelane_b32 v252, s47, 47
	v_writelane_b32 v252, s48, 48
	v_writelane_b32 v252, s49, 49
	v_writelane_b32 v252, s50, 50
	v_writelane_b32 v252, s51, 51
	v_writelane_b32 v252, s52, 52
	v_writelane_b32 v252, s53, 53
	v_writelane_b32 v252, s54, 54
	v_writelane_b32 v252, s55, 55
	v_writelane_b32 v252, s56, 56
	v_writelane_b32 v252, s57, 57
	v_writelane_b32 v252, s58, 58
	v_writelane_b32 v252, s59, 59
	v_writelane_b32 v252, s60, 60
	v_writelane_b32 v252, s61, 61
	v_writelane_b32 v252, s62, 62
	v_writelane_b32 v252, s63, 63
	v_writelane_b32 v253, s64, 0
	v_writelane_b32 v253, s65, 1
	v_writelane_b32 v253, s66, 2
	v_writelane_b32 v253, s67, 3
	v_writelane_b32 v253, s68, 4
	v_writelane_b32 v253, s69, 5
	v_writelane_b32 v253, s70, 6
	v_writelane_b32 v253, s71, 7
	v_writelane_b32 v253, s72, 8
	v_writelane_b32 v253, s73, 9
	v_writelane_b32 v253, s74, 10
	v_writelane_b32 v253, s75, 11
	v_writelane_b32 v253, s76, 12
	v_writelane_b32 v253, s77, 13
	v_writelane_b32 v253, s78, 14
	v_writelane_b32 v253, s79, 15
	v_writelane_b32 v253, s80, 16
	v_writelane_b32 v253, s81, 17
	v_writelane_b32 v253, s82, 18
	v_writelane_b32 v253, s83, 19
	v_writelane_b32 v253, s84, 20
	v_writelane_b32 v253, s85, 21
	v_writelane_b32 v253, s86, 22
	v_writelane_b32 v253, s87, 23
	v_writelane_b32 v253, s88, 24
	v_writelane_b32 v253, s89, 25
	v_writelane_b32 v253, s90, 26
	v_writelane_b32 v253, s91, 27
	v_writelane_b32 v253, s92, 28
	v_writelane_b32 v253, s93, 29
	v_writelane_b32 v253, s94, 30
	v_writelane_b32 v253, s95, 31
	v_writelane_b32 v253, s96, 32
	v_writelane_b32 v253, s97, 33
	s_mov_b32 s100, 4
	s_mov_b32 s98, 0x89ff
	v_and_b32_e32 v237, 63, v178
	v_readlane_b32 s99, v255, 13
	v_readfirstlane_b32 s37, v178
	s_nop 4
	s_sub_i32 s101, s34, 172
	s_lshl_b32 s101, s101, 3
	s_add_i32 s99, s99, s101
	s_add_i32 s30, s99, 0x7400
	s_movk_i32 s86, 672
	s_branch .Lcv_hop_entry
